# ssd_norm: next item's y/z loads issued before the current item is processed (software prefetch, was load-wait-compute-store per item)
# baseline (speedup 1.0000x reference)
; __device__ __forceinline__ int tid_() { int t = (int)threadIdx.x; asm volatile("" : "+v"(t)); return t & 511; }
; __device__ __forceinline__ int bid_() { int b = (int)blockIdx.x; asm volatile("" : "+s"(b)); return b; }
; __device__ __forceinline__ int gdim_() { int g = (int)gridDim.x; asm volatile("" : "+s"(g)); return g; }
; DI void ssd_norm(const Params& P) {
;     unsigned char* ws = P.ws; const int tid = tid_(), lane = tid & 63; const int gw = bid_() * 8 + (tid >> 6), NW = gdim_() * 8;
;     bf16_t* YB = (bf16_t*)(ws + O_R + R_YBUF); const bf16_t* Z = (const bf16_t*)(ws + O_R + R_Z);
; #pragma unroll 4
;     for (int item = gw; item < T * 4; item += NW) { const size_t off = (size_t)(item >> 2) * 2048 + (item & 3) * 512 + lane * 8;
.LBB0_164:
	v_mov_b32_e32 v0, v167
	s_waitcnt lgkmcnt(0)
	v_readlane_b32 s10, v254, 0
	v_bfe_u32 v8, v0, 6, 3
	s_mov_b32 s3, 0x10800
	v_lshl_or_b32 v1, s10, 3, v8
	s_load_dword s11, s[50:51], 0x0
	v_cmp_gt_i32_e32 vcc, s3, v1
	s_waitcnt lgkmcnt(0)
	s_and_saveexec_b64 s[4:5], vcc
	s_cbranch_execz .LBB0_167
	v_and_b32_e32 v2, 64, v187
	v_add_u32_e32 v7, 64, v2
	v_xor_b32_e32 v2, 32, v187
	v_cmp_lt_i32_e32 vcc, v2, v7
	v_xor_b32_e32 v3, 16, v187
	v_xor_b32_e32 v4, 8, v187
	v_cndmask_b32_e32 v2, v187, v2, vcc
	v_cmp_lt_i32_e32 vcc, v3, v7
	v_xor_b32_e32 v5, 4, v187
	s_lshl_b32 s3, s11, 3
	v_cndmask_b32_e32 v3, v187, v3, vcc
	v_cmp_lt_i32_e32 vcc, v4, v7
	v_xor_b32_e32 v6, 2, v187
	s_add_u32 s6, s26, 0x16560000
	v_cndmask_b32_e32 v4, v187, v4, vcc
	v_cmp_lt_i32_e32 vcc, v5, v7
	v_xor_b32_e32 v9, 1, v187
	v_and_b32_e32 v0, 0x1ff, v0
	v_cndmask_b32_e32 v5, v187, v5, vcc
	v_cmp_lt_i32_e32 vcc, v6, v7
	s_addc_u32 s7, s27, 0
	s_add_u32 s8, s26, 0x1a760000
	v_cndmask_b32_e32 v6, v187, v6, vcc
	v_cmp_lt_i32_e32 vcc, v9, v7
	v_lshlrev_b32_e32 v0, 3, v0
	v_lshlrev_b32_e32 v8, 9, v8
	v_cndmask_b32_e32 v7, v187, v9, vcc
	s_addc_u32 s9, s27, 0
	v_and_b32_e32 v0, 0x1f8, v0
	v_lshlrev_b32_e32 v2, 2, v2
	v_lshlrev_b32_e32 v3, 2, v3
	v_lshlrev_b32_e32 v4, 2, v4
	v_lshlrev_b32_e32 v5, 2, v5
	v_lshlrev_b32_e32 v6, 2, v6
	v_lshlrev_b32_e32 v7, 2, v7
	v_lshl_or_b32 v8, s10, 12, v8
	s_lshl_b32 s12, s11, 12
	s_mov_b64 s[10:11], 0
	v_ashrrev_i32_e32 v44, 2, v1
	v_ashrrev_i32_e32 v45, 31, v44
	v_lshlrev_b64 v[44:45], 11, v[44:45]
	s_movk_i32 s13, 0x600
	v_and_or_b32 v46, v8, s13, v44
	v_or_b32_e32 v44, v46, v0
	v_lshlrev_b64 v[42:43], 1, v[44:45]
	v_lshl_add_u64 v[40:41], s[8:9], 0, v[42:43]
	v_lshl_add_u64 v[42:43], s[6:7], 0, v[42:43]
	global_load_dwordx4 v[32:35], v[40:41], off
	global_load_dwordx4 v[36:39], v[42:43], off
	s_waitcnt vmcnt(0)
	s_branch .Lnorm_top

; DI float siluf_(float x) { return x * sigmoidf_(x); }
; DI void unpack8(const u32x4& w, float* f) { f[0] = bflo(w.x); f[1] = bfhi(w.x); f[2] = bflo(w.y); f[3] = bfhi(w.y); f[4] = bflo(w.z); f[5] = bfhi(w.z); f[6] = bflo(w.w); f[7] = bfhi(w.w); }
; DI u32x4 pack8(const float* f) { u32x4 w; w.x = pk2(f[0], f[1]); w.y = pk2(f[2], f[3]); w.z = pk2(f[4], f[5]); w.w = pk2(f[6], f[7]); return w; }
; DI float rs_of(float ss, float inv_n) { return __builtin_amdgcn_rsqf(ss * inv_n + EPS); }
; DI void ssd_norm(const Params& P) {
;     ...
;     for (int item = gw; item < T * 4; item += NW) { const size_t off = (size_t)(item >> 2) * 2048 + (item & 3) * 512 + lane * 8;
;         const u32x4 yw = *(const u32x4*)(YB + off), zw = *(const u32x4*)(Z + off); float f[8], z[8]; unpack8(yw, f); unpack8(zw, z);
;         float sq = 0.f;
; #pragma unroll
;         for (int j = 0; j < 8; ++j) { f[j] *= siluf_(z[j]); sq += f[j] * f[j]; }
; #pragma unroll
;         for (int o = 32; o >= 1; o >>= 1) sq += __shfl_xor(sq, o);
;         const float rs = rs_of(sq, 1.f / 512.f);
; #pragma unroll
;         for (int j = 0; j < 8; ++j) f[j] *= rs;
;         *(u32x4*)(YB + off) = pack8(f); }
.Lnorm_top:
	v_mov_b32_e32 v10, v32
	v_mov_b32_e32 v11, v33
	v_mov_b32_e32 v12, v34
	v_mov_b32_e32 v13, v35
	v_mov_b32_e32 v14, v36
	v_mov_b32_e32 v15, v37
	v_mov_b32_e32 v16, v38
	v_mov_b32_e32 v17, v39
	v_mov_b32_e32 v18, v40
	v_mov_b32_e32 v19, v41
	v_add_u32_e32 v1, s3, v1
	s_mov_b32 s13, 0x107ff
	v_cmp_lt_i32_e32 vcc, s13, v1
	v_add_u32_e32 v8, s12, v8
	s_or_b64 s[10:11], vcc, s[10:11]
	s_and_b64 vcc, exec, vcc
	s_cbranch_vccnz .Lnorm_nopf
	v_ashrrev_i32_e32 v44, 2, v1
	v_ashrrev_i32_e32 v45, 31, v44
	v_lshlrev_b64 v[44:45], 11, v[44:45]
	s_movk_i32 s13, 0x600
	v_and_or_b32 v46, v8, s13, v44
	v_or_b32_e32 v44, v46, v0
	v_lshlrev_b64 v[42:43], 1, v[44:45]
	v_lshl_add_u64 v[40:41], s[8:9], 0, v[42:43]
	v_lshl_add_u64 v[42:43], s[6:7], 0, v[42:43]
	global_load_dwordx4 v[32:35], v[40:41], off
	global_load_dwordx4 v[36:39], v[42:43], off
.Lnorm_nopf:
	v_lshlrev_b32_e32 v20, 16, v13
	v_and_b32_e32 v21, 0xffff0000, v13
	v_lshlrev_b32_e32 v22, 16, v17
	v_mul_f32_e32 v9, 0xbfb8aa3b, v22
	v_exp_f32_e32 v9, v9
	v_and_b32_e32 v23, 0xffff0000, v17
	v_and_b32_e32 v13, 0xffff0000, v16
	v_lshlrev_b32_e32 v28, 16, v15
	v_add_f32_e32 v9, 1.0, v9
	v_rcp_f32_e32 v26, v9
	v_mul_f32_e32 v9, 0xbfb8aa3b, v23
	v_exp_f32_e32 v9, v9
	v_and_b32_e32 v29, 0xffff0000, v15
	v_add_f32_e32 v9, 1.0, v9
	v_rcp_f32_e32 v27, v9
	s_nop 0
	v_pk_mul_f32 v[22:23], v[26:27], v[22:23]
	v_lshlrev_b32_e32 v26, 16, v12
	v_and_b32_e32 v27, 0xffff0000, v12
	v_lshlrev_b32_e32 v12, 16, v16
	v_mul_f32_e32 v9, 0xbfb8aa3b, v12
	v_exp_f32_e32 v9, v9
	v_pk_mul_f32 v[20:21], v[22:23], v[20:21]
	v_add_f32_e32 v9, 1.0, v9
	v_rcp_f32_e32 v16, v9
	v_mul_f32_e32 v9, 0xbfb8aa3b, v13
	v_exp_f32_e32 v9, v9
	v_pk_mul_f32 v[22:23], v[20:21], v[20:21]
	v_add_f32_e32 v9, 1.0, v9
	v_rcp_f32_e32 v17, v9
	v_mul_f32_e32 v9, 0xbfb8aa3b, v28
	v_exp_f32_e32 v9, v9
	v_pk_mul_f32 v[12:13], v[16:17], v[12:13]
	s_nop 0
	v_pk_mul_f32 v[12:13], v[12:13], v[26:27]
	v_add_f32_e32 v9, 1.0, v9
	v_rcp_f32_e32 v30, v9
	v_mul_f32_e32 v9, 0xbfb8aa3b, v29
	v_exp_f32_e32 v9, v9
	v_lshlrev_b32_e32 v26, 16, v11
	v_and_b32_e32 v27, 0xffff0000, v11
	v_and_b32_e32 v11, 0xffff0000, v14
	v_add_f32_e32 v9, 1.0, v9
	v_rcp_f32_e32 v31, v9
	v_pk_mul_f32 v[16:17], v[12:13], v[12:13]
	v_pk_mul_f32 v[28:29], v[30:31], v[28:29]
	v_lshlrev_b32_e32 v30, 16, v10
	v_and_b32_e32 v31, 0xffff0000, v10
	v_lshlrev_b32_e32 v10, 16, v14
	v_mul_f32_e32 v9, 0xbfb8aa3b, v10
	v_exp_f32_e32 v9, v9
	v_pk_mul_f32 v[26:27], v[28:29], v[26:27]
	v_add_f32_e32 v9, 1.0, v9
	v_rcp_f32_e32 v14, v9
	v_mul_f32_e32 v9, 0xbfb8aa3b, v11
	v_exp_f32_e32 v9, v9
	v_pk_mul_f32 v[28:29], v[26:27], v[26:27]
	v_add_f32_e32 v9, 1.0, v9
	v_rcp_f32_e32 v15, v9
	s_nop 0
	v_pk_mul_f32 v[10:11], v[14:15], v[10:11]
	s_nop 0
	v_pk_mul_f32 v[10:11], v[10:11], v[30:31]
	s_nop 0
	v_pk_mul_f32 v[14:15], v[10:11], v[10:11]
	s_nop 0
	v_add_f32_e32 v9, v14, v15
	v_add_f32_e32 v9, v28, v9
	v_add_f32_e32 v9, v29, v9
	v_add_f32_e32 v9, v16, v9
	v_add_f32_e32 v9, v17, v9
	v_add_f32_e32 v9, v22, v9
	v_add_f32_e32 v9, v23, v9
	ds_bpermute_b32 v14, v2, v9
	s_waitcnt lgkmcnt(0)
	v_add_f32_e32 v9, v9, v14
	ds_bpermute_b32 v14, v3, v9
	s_waitcnt lgkmcnt(0)
	v_add_f32_e32 v9, v9, v14
	ds_bpermute_b32 v14, v4, v9
	s_waitcnt lgkmcnt(0)
	v_add_f32_e32 v9, v9, v14
	ds_bpermute_b32 v14, v5, v9
	s_waitcnt lgkmcnt(0)
	v_add_f32_e32 v9, v9, v14
	ds_bpermute_b32 v14, v6, v9
	s_waitcnt lgkmcnt(0)
	v_add_f32_e32 v9, v9, v14
	ds_bpermute_b32 v14, v7, v9
	s_waitcnt lgkmcnt(0)
	v_add_f32_e32 v9, v9, v14
	v_fmamk_f32 v9, v9, 0x3b000000, v185
	v_rsq_f32_e32 v14, v9
	s_nop 0
	v_pk_mul_f32 v[10:11], v[10:11], v[14:15] op_sel_hi:[1,0]
	v_pk_mul_f32 v[16:17], v[26:27], v[14:15] op_sel_hi:[1,0]
	v_pk_mul_f32 v[12:13], v[12:13], v[14:15] op_sel_hi:[1,0]
	v_pk_mul_f32 v[14:15], v[20:21], v[14:15] op_sel_hi:[1,0]
	v_cvt_pk_bf16_f32 v10, v10, v11
	v_cvt_pk_bf16_f32 v11, v16, v17
	v_cvt_pk_bf16_f32 v12, v12, v13
	v_cvt_pk_bf16_f32 v13, v14, v15
	global_store_dwordx4 v[18:19], v[10:13], off
	s_andn2_b64 exec, exec, s[10:11]
	s_cbranch_execnz .LBB0_166
